# GEMM accumulators zeroed with 63 v_mov_b64 instead of 127 v_mov_b32 per unit
# speedup vs baseline: 1.0078x; 1.0078x over previous
;   __device__ __forceinline__ const char* aptr(const Unit& u) const { return s.aptr(u); }
;   __device__ __forceinline__ const char* bptr(const Unit& u) const { return s.bptr(u); }
;   __device__ __forceinline__ bool next(int i, Unit& u) const { if (i) return false; u = u0; return true; }
; template <class Epi, class Sched>
; __device__ __forceinline__ void gemm_phase(PG8_LAS unsigned char* lds, const int lda, const int ldb, const Sched& S, const Epi& E) {
;     ...
;     const bool has_next = S.next(ui + 1, nxt);
;     const char* nA = has_next ? S.aptr(nxt) : cA; const char* nB = has_next ? S.bptr(nxt) : cB;
; #pragma unroll 1
;     for (int t = 0; t < nt; t += 2) {
;       const bool last = (t == nt - 2);
;       const char* a1 = cA + (size_t)(t + 1) * kstep;
;       const char* a2 = last ? nA : cA + (size_t)(t + 2) * kstep; const char* b2 = last ? nB : cB + (size_t)(t + 2) * kstep;
;       const char* a3 = a2 + kstep; const char* b3 = b2 + kstep;
;     ...
; #pragma unroll
;     for (int a = 0; a < 2; ++a)
; #pragma unroll
;       for (int b = 0; b < 2; ++b)
; #pragma unroll
;         for (int m = 0; m < 4; ++m)
; #pragma unroll
;           for (int n = 0; n < 2; ++n) acc[a][b][m][n] = (f32x4){0.f, 0.f, 0.f, 0.f};
.LBB0_334:
	s_ashr_i32 s17, s16, 31
	s_xor_b64 s[20:21], s[24:25], -1
	s_lshl_b64 s[18:19], s[16:17], 19
	s_add_u32 s18, s58, s18
	s_addc_u32 s19, s59, s19
	s_and_b64 s[22:23], s[24:25], exec
	s_cselect_b32 s17, s19, s9
	s_cselect_b32 s26, s18, s8
	s_ashr_i32 s15, s14, 31
	s_lshl_b64 s[22:23], s[14:15], 19
	v_readlane_b32 s15, v255, 29
	s_add_u32 s22, s15, s22
	v_readlane_b32 s15, v255, 30
	s_addc_u32 s23, s15, s23
	s_and_b64 s[24:25], s[24:25], exec
	s_cselect_b32 s15, s23, s11
	s_cselect_b32 s27, s22, s10
	s_add_u32 s8, s8, 0x40080
	s_addc_u32 s9, s9, 0
	s_add_u32 s28, s10, 0x100
	v_mov_b32_e32 v2, 0
	s_addc_u32 s29, s11, 0
	s_mov_b32 s30, -2
	v_mov_b32_e32 v3, v2
	v_mov_b64_e32 v[4:5], 0
	v_mov_b64_e32 v[6:7], 0
	v_mov_b64_e32 v[8:9], 0
	v_mov_b64_e32 v[10:11], 0
	v_mov_b64_e32 v[12:13], 0
	v_mov_b64_e32 v[14:15], 0
	v_mov_b64_e32 v[16:17], 0
	v_mov_b64_e32 v[18:19], 0
	v_mov_b64_e32 v[20:21], 0
	v_mov_b64_e32 v[22:23], 0
	v_mov_b64_e32 v[24:25], 0
	v_mov_b64_e32 v[26:27], 0
	v_mov_b64_e32 v[28:29], 0
	v_mov_b64_e32 v[30:31], 0
	v_mov_b64_e32 v[32:33], 0
	v_mov_b64_e32 v[34:35], 0
	v_mov_b64_e32 v[36:37], 0
	v_mov_b64_e32 v[38:39], 0
	v_mov_b64_e32 v[40:41], 0
	v_mov_b64_e32 v[42:43], 0
	v_mov_b64_e32 v[44:45], 0
	v_mov_b64_e32 v[46:47], 0
	v_mov_b64_e32 v[48:49], 0
	v_mov_b64_e32 v[50:51], 0
	v_mov_b64_e32 v[52:53], 0
	v_mov_b64_e32 v[54:55], 0
	v_mov_b64_e32 v[56:57], 0
	v_mov_b64_e32 v[58:59], 0
	v_mov_b64_e32 v[60:61], 0
	v_mov_b64_e32 v[62:63], 0
	v_mov_b64_e32 v[64:65], 0
	v_mov_b64_e32 v[66:67], 0
	v_mov_b64_e32 v[68:69], 0
	v_mov_b64_e32 v[70:71], 0
	v_mov_b64_e32 v[72:73], 0
	v_mov_b64_e32 v[74:75], 0
	v_mov_b64_e32 v[76:77], 0
	v_mov_b64_e32 v[78:79], 0
	v_mov_b64_e32 v[80:81], 0
	v_mov_b64_e32 v[82:83], 0
	v_mov_b64_e32 v[84:85], 0
	v_mov_b64_e32 v[86:87], 0
	v_mov_b64_e32 v[88:89], 0
	v_mov_b64_e32 v[90:91], 0
	v_mov_b64_e32 v[92:93], 0
	v_mov_b64_e32 v[94:95], 0
	v_mov_b64_e32 v[96:97], 0
	v_mov_b64_e32 v[98:99], 0
	v_mov_b64_e32 v[100:101], 0
	v_mov_b64_e32 v[102:103], 0
	v_mov_b64_e32 v[104:105], 0
	v_mov_b64_e32 v[106:107], 0
	v_mov_b64_e32 v[108:109], 0
	v_mov_b64_e32 v[110:111], 0
	v_mov_b64_e32 v[112:113], 0
	v_mov_b64_e32 v[114:115], 0
	v_mov_b64_e32 v[116:117], 0
	v_mov_b64_e32 v[118:119], 0
	v_mov_b64_e32 v[120:121], 0
	v_mov_b64_e32 v[122:123], 0
	v_mov_b64_e32 v[124:125], 0
	v_mov_b64_e32 v[126:127], 0
	v_mov_b64_e32 v[128:129], 0

;   __device__ __forceinline__ const char* aptr(const Unit& u) const { return s.aptr(u); }
;   __device__ __forceinline__ const char* bptr(const Unit& u) const { return s.bptr(u); }
;   __device__ __forceinline__ bool next(int i, Unit& u) const { if (i) return false; u = u0; return true; }
; template <class Epi, class Sched>
; __device__ __forceinline__ void gemm_phase(PG8_LAS unsigned char* lds, const int lda, const int ldb, const Sched& S, const Epi& E) {
;     ...
;     const bool has_next = S.next(ui + 1, nxt);
;     const char* nA = has_next ? S.aptr(nxt) : cA; const char* nB = has_next ? S.bptr(nxt) : cB;
; #pragma unroll 1
;     for (int t = 0; t < nt; t += 2) {
;       const bool last = (t == nt - 2);
;       const char* a1 = cA + (size_t)(t + 1) * kstep;
;       const char* a2 = last ? nA : cA + (size_t)(t + 2) * kstep; const char* b2 = last ? nB : cB + (size_t)(t + 2) * kstep;
;       const char* a3 = a2 + kstep; const char* b3 = b2 + kstep;
;     ...
; #pragma unroll
;     for (int a = 0; a < 2; ++a)
; #pragma unroll
;       for (int b = 0; b < 2; ++b)
; #pragma unroll
;         for (int m = 0; m < 4; ++m)
; #pragma unroll
;           for (int n = 0; n < 2; ++n) acc[a][b][m][n] = (f32x4){0.f, 0.f, 0.f, 0.f};
.LBB0_684:
	v_mov_b64_e32 v[2:3], 0xa20
	s_ashr_i32 s19, s18, 31
	v_cmp_lt_i64_e32 vcc, s[20:21], v[2:3]
	s_lshl_b64 s[20:21], s[18:19], 19
	s_add_u32 s20, s58, s20
	s_addc_u32 s21, s59, s21
	s_and_b64 s[22:23], vcc, exec
	s_cselect_b32 s19, s21, s11
	s_cselect_b32 s26, s20, s10
	s_ashr_i32 s17, s16, 31
	s_lshl_b64 s[22:23], s[16:17], 19
	v_readlane_b32 s17, v255, 29
	s_add_u32 s22, s17, s22
	v_readlane_b32 s17, v255, 30
	s_addc_u32 s23, s17, s23
	s_and_b64 s[24:25], vcc, exec
	s_cselect_b32 s17, s23, s13
	s_cselect_b32 s27, s22, s12
	s_add_u32 s10, s10, 0x40080
	s_addc_u32 s11, s11, 0
	s_add_u32 s28, s12, 0x100
	v_mov_b32_e32 v2, 0
	s_addc_u32 s29, s13, 0
	s_mov_b32 s30, -2
	v_mov_b32_e32 v3, v2
	v_mov_b64_e32 v[4:5], 0
	v_mov_b64_e32 v[6:7], 0
	v_mov_b64_e32 v[8:9], 0
	v_mov_b64_e32 v[10:11], 0
	v_mov_b64_e32 v[12:13], 0
	v_mov_b64_e32 v[14:15], 0
	v_mov_b64_e32 v[16:17], 0
	v_mov_b64_e32 v[18:19], 0
	v_mov_b64_e32 v[20:21], 0
	v_mov_b64_e32 v[22:23], 0
	v_mov_b64_e32 v[24:25], 0
	v_mov_b64_e32 v[26:27], 0
	v_mov_b64_e32 v[28:29], 0
	v_mov_b64_e32 v[30:31], 0
	v_mov_b64_e32 v[32:33], 0
	v_mov_b64_e32 v[34:35], 0
	v_mov_b64_e32 v[36:37], 0
	v_mov_b64_e32 v[38:39], 0
	v_mov_b64_e32 v[40:41], 0
	v_mov_b64_e32 v[42:43], 0
	v_mov_b64_e32 v[44:45], 0
	v_mov_b64_e32 v[46:47], 0
	v_mov_b64_e32 v[48:49], 0
	v_mov_b64_e32 v[50:51], 0
	v_mov_b64_e32 v[52:53], 0
	v_mov_b64_e32 v[54:55], 0
	v_mov_b64_e32 v[56:57], 0
	v_mov_b64_e32 v[58:59], 0
	v_mov_b64_e32 v[60:61], 0
	v_mov_b64_e32 v[62:63], 0
	v_mov_b64_e32 v[64:65], 0
	v_mov_b64_e32 v[66:67], 0
	v_mov_b64_e32 v[68:69], 0
	v_mov_b64_e32 v[70:71], 0
	v_mov_b64_e32 v[72:73], 0
	v_mov_b64_e32 v[74:75], 0
	v_mov_b64_e32 v[76:77], 0
	v_mov_b64_e32 v[78:79], 0
	v_mov_b64_e32 v[80:81], 0
	v_mov_b64_e32 v[82:83], 0
	v_mov_b64_e32 v[84:85], 0
	v_mov_b64_e32 v[86:87], 0
	v_mov_b64_e32 v[88:89], 0
	v_mov_b64_e32 v[90:91], 0
	v_mov_b64_e32 v[92:93], 0
	v_mov_b64_e32 v[94:95], 0
	v_mov_b64_e32 v[96:97], 0
	v_mov_b64_e32 v[98:99], 0
	v_mov_b64_e32 v[100:101], 0
	v_mov_b64_e32 v[102:103], 0
	v_mov_b64_e32 v[104:105], 0
	v_mov_b64_e32 v[106:107], 0
	v_mov_b64_e32 v[108:109], 0
	v_mov_b64_e32 v[110:111], 0
	v_mov_b64_e32 v[112:113], 0
	v_mov_b64_e32 v[114:115], 0
	v_mov_b64_e32 v[116:117], 0
	v_mov_b64_e32 v[118:119], 0
	v_mov_b64_e32 v[120:121], 0
	v_mov_b64_e32 v[122:123], 0
	v_mov_b64_e32 v[124:125], 0
	v_mov_b64_e32 v[126:127], 0
	v_mov_b64_e32 v[128:129], 0

;   __device__ __forceinline__ const char* aptr(const Unit& u) const { return s.aptr(u); }
;   __device__ __forceinline__ const char* bptr(const Unit& u) const { return s.bptr(u); }
;   __device__ __forceinline__ bool next(int i, Unit& u) const { if (i) return false; u = u0; return true; }
; template <class Epi, class Sched>
; __device__ __forceinline__ void gemm_phase(PG8_LAS unsigned char* lds, const int lda, const int ldb, const Sched& S, const Epi& E) {
;     ...
;     const bool has_next = S.next(ui + 1, nxt);
;     const char* nA = has_next ? S.aptr(nxt) : cA; const char* nB = has_next ? S.bptr(nxt) : cB;
; #pragma unroll 1
;     for (int t = 0; t < nt; t += 2) {
;       const bool last = (t == nt - 2);
;       const char* a1 = cA + (size_t)(t + 1) * kstep;
;       const char* a2 = last ? nA : cA + (size_t)(t + 2) * kstep; const char* b2 = last ? nB : cB + (size_t)(t + 2) * kstep;
;       const char* a3 = a2 + kstep; const char* b3 = b2 + kstep;
;     ...
; #pragma unroll
;     for (int a = 0; a < 2; ++a)
; #pragma unroll
;       for (int b = 0; b < 2; ++b)
; #pragma unroll
;         for (int m = 0; m < 4; ++m)
; #pragma unroll
;           for (int n = 0; n < 2; ++n) acc[a][b][m][n] = (f32x4){0.f, 0.f, 0.f, 0.f};
.LBB0_1087:
	v_mov_b64_e32 v[2:3], 0x100
	s_ashr_i32 s7, s6, 31
	v_cmp_lt_i64_e32 vcc, s[8:9], v[2:3]
	s_lshl_b64 s[8:9], s[6:7], 21
	v_readlane_b32 s1, v254, 41
	s_add_u32 s8, s1, s8
	v_readlane_b32 s1, v254, 42
	s_addc_u32 s9, s1, s9
	s_and_b64 s[10:11], vcc, exec
	s_cselect_b32 s7, s9, s15
	s_cselect_b32 s13, s8, s14
	s_ashr_i32 s1, s0, 31
	s_lshl_b64 s[10:11], s[0:1], 21
	s_add_u32 s10, s69, s10
	v_readlane_b32 s1, v254, 40
	s_addc_u32 s11, s1, s11
	s_and_b64 s[18:19], vcc, exec
	s_cselect_b32 s1, s11, s17
	s_cselect_b32 s29, s10, s16
	s_add_u32 s14, s14, 0x100080
	s_addc_u32 s15, s15, 0
	s_add_u32 s30, s16, 0x100
	v_mov_b32_e32 v2, 0
	s_addc_u32 s31, s17, 0
	s_mov_b32 s34, -2
	v_mov_b32_e32 v3, v2
	v_mov_b64_e32 v[4:5], 0
	v_mov_b64_e32 v[6:7], 0
	v_mov_b64_e32 v[8:9], 0
	v_mov_b64_e32 v[10:11], 0
	v_mov_b64_e32 v[12:13], 0
	v_mov_b64_e32 v[14:15], 0
	v_mov_b64_e32 v[16:17], 0
	v_mov_b64_e32 v[18:19], 0
	v_mov_b64_e32 v[20:21], 0
	v_mov_b64_e32 v[22:23], 0
	v_mov_b64_e32 v[24:25], 0
	v_mov_b64_e32 v[26:27], 0
	v_mov_b64_e32 v[28:29], 0
	v_mov_b64_e32 v[30:31], 0
	v_mov_b64_e32 v[32:33], 0
	v_mov_b64_e32 v[34:35], 0
	v_mov_b64_e32 v[36:37], 0
	v_mov_b64_e32 v[38:39], 0
	v_mov_b64_e32 v[40:41], 0
	v_mov_b64_e32 v[42:43], 0
	v_mov_b64_e32 v[44:45], 0
	v_mov_b64_e32 v[46:47], 0
	v_mov_b64_e32 v[48:49], 0
	v_mov_b64_e32 v[50:51], 0
	v_mov_b64_e32 v[52:53], 0
	v_mov_b64_e32 v[54:55], 0
	v_mov_b64_e32 v[56:57], 0
	v_mov_b64_e32 v[58:59], 0
	v_mov_b64_e32 v[60:61], 0
	v_mov_b64_e32 v[62:63], 0
	v_mov_b64_e32 v[64:65], 0
	v_mov_b64_e32 v[66:67], 0
	v_mov_b64_e32 v[68:69], 0
	v_mov_b64_e32 v[70:71], 0
	v_mov_b64_e32 v[72:73], 0
	v_mov_b64_e32 v[74:75], 0
	v_mov_b64_e32 v[76:77], 0
	v_mov_b64_e32 v[78:79], 0
	v_mov_b64_e32 v[80:81], 0
	v_mov_b64_e32 v[82:83], 0
	v_mov_b64_e32 v[84:85], 0
	v_mov_b64_e32 v[86:87], 0
	v_mov_b64_e32 v[88:89], 0
	v_mov_b64_e32 v[90:91], 0
	v_mov_b64_e32 v[92:93], 0
	v_mov_b64_e32 v[94:95], 0
	v_mov_b64_e32 v[96:97], 0
	v_mov_b64_e32 v[98:99], 0
	v_mov_b64_e32 v[100:101], 0
	v_mov_b64_e32 v[102:103], 0
	v_mov_b64_e32 v[104:105], 0
	v_mov_b64_e32 v[106:107], 0
	v_mov_b64_e32 v[108:109], 0
	v_mov_b64_e32 v[110:111], 0
	v_mov_b64_e32 v[112:113], 0
	v_mov_b64_e32 v[114:115], 0
	v_mov_b64_e32 v[116:117], 0
	v_mov_b64_e32 v[118:119], 0
	v_mov_b64_e32 v[120:121], 0
	v_mov_b64_e32 v[122:123], 0
	v_mov_b64_e32 v[124:125], 0
	v_mov_b64_e32 v[126:127], 0
	v_mov_b64_e32 v[128:129], 0

;   __device__ __forceinline__ int kt(const Unit& u) const { return ((u.pn & 7) < 4) ? 4 : 16; }
; template <class Epi, class Sched>
; __device__ __forceinline__ void gemm_phase(PG8_LAS unsigned char* lds, const int lda, const int ldb, const Sched& S, const Epi& E) {
;     ...
; #pragma unroll
;     for (int a = 0; a < 2; ++a)
; #pragma unroll
;       for (int b = 0; b < 2; ++b)
; #pragma unroll
;         for (int m = 0; m < 4; ++m)
; #pragma unroll
;           for (int n = 0; n < 2; ++n) acc[a][b][m][n] = (f32x4){0.f, 0.f, 0.f, 0.f};
;     cur = nxt; cA = nA; cB = nB; ++ui;
;     nt = S.kt(cur);
.LBB0_1411:
	s_add_i32 s11, s43, -2
	s_add_u32 s14, s14, 0x40080
	s_addc_u32 s15, s15, 0
	s_add_u32 s22, s18, 0x100
	v_mov_b32_e32 v2, 0
	s_addc_u32 s23, s19, 0
	s_mov_b32 s18, 0
	v_mov_b32_e32 v3, v2
	v_mov_b64_e32 v[4:5], 0
	v_mov_b64_e32 v[6:7], 0
	v_mov_b64_e32 v[8:9], 0
	v_mov_b64_e32 v[10:11], 0
	v_mov_b64_e32 v[12:13], 0
	v_mov_b64_e32 v[14:15], 0
	v_mov_b64_e32 v[16:17], 0
	v_mov_b64_e32 v[18:19], 0
	v_mov_b64_e32 v[20:21], 0
	v_mov_b64_e32 v[22:23], 0
	v_mov_b64_e32 v[24:25], 0
	v_mov_b64_e32 v[26:27], 0
	v_mov_b64_e32 v[28:29], 0
	v_mov_b64_e32 v[30:31], 0
	v_mov_b64_e32 v[32:33], 0
	v_mov_b64_e32 v[34:35], 0
	v_mov_b64_e32 v[36:37], 0
	v_mov_b64_e32 v[38:39], 0
	v_mov_b64_e32 v[40:41], 0
	v_mov_b64_e32 v[42:43], 0
	v_mov_b64_e32 v[44:45], 0
	v_mov_b64_e32 v[46:47], 0
	v_mov_b64_e32 v[48:49], 0
	v_mov_b64_e32 v[50:51], 0
	v_mov_b64_e32 v[52:53], 0
	v_mov_b64_e32 v[54:55], 0
	v_mov_b64_e32 v[56:57], 0
	v_mov_b64_e32 v[58:59], 0
	v_mov_b64_e32 v[60:61], 0
	v_mov_b64_e32 v[62:63], 0
	v_mov_b64_e32 v[64:65], 0
	v_mov_b64_e32 v[66:67], 0
	v_mov_b64_e32 v[68:69], 0
	v_mov_b64_e32 v[70:71], 0
	v_mov_b64_e32 v[72:73], 0
	v_mov_b64_e32 v[74:75], 0
	v_mov_b64_e32 v[76:77], 0
	v_mov_b64_e32 v[78:79], 0
	v_mov_b64_e32 v[80:81], 0
	v_mov_b64_e32 v[82:83], 0
	v_mov_b64_e32 v[84:85], 0
	v_mov_b64_e32 v[86:87], 0
	v_mov_b64_e32 v[88:89], 0
	v_mov_b64_e32 v[90:91], 0
	v_mov_b64_e32 v[92:93], 0
	v_mov_b64_e32 v[94:95], 0
	v_mov_b64_e32 v[96:97], 0
	v_mov_b64_e32 v[98:99], 0
	v_mov_b64_e32 v[100:101], 0
	v_mov_b64_e32 v[102:103], 0
	v_mov_b64_e32 v[104:105], 0
	v_mov_b64_e32 v[106:107], 0
	v_mov_b64_e32 v[108:109], 0
	v_mov_b64_e32 v[110:111], 0
	v_mov_b64_e32 v[112:113], 0
	v_mov_b64_e32 v[114:115], 0
	v_mov_b64_e32 v[116:117], 0
	v_mov_b64_e32 v[118:119], 0
	v_mov_b64_e32 v[120:121], 0
	v_mov_b64_e32 v[122:123], 0
	v_mov_b64_e32 v[124:125], 0
	v_mov_b64_e32 v[126:127], 0
	v_mov_b64_e32 v[128:129], 0

;   __device__ __forceinline__ const char* aptr(const Unit& u) const { return s.aptr(u); }
;   __device__ __forceinline__ const char* bptr(const Unit& u) const { return s.bptr(u); }
;   __device__ __forceinline__ bool next(int i, Unit& u) const { if (i) return false; u = u0; return true; }
; template <class Epi, class Sched>
; __device__ __forceinline__ void gemm_phase(PG8_LAS unsigned char* lds, const int lda, const int ldb, const Sched& S, const Epi& E) {
;     ...
;     const bool has_next = S.next(ui + 1, nxt);
;     const char* nA = has_next ? S.aptr(nxt) : cA; const char* nB = has_next ? S.bptr(nxt) : cB;
; #pragma unroll 1
;     for (int t = 0; t < nt; t += 2) {
;       const bool last = (t == nt - 2);
;       const char* a1 = cA + (size_t)(t + 1) * kstep;
;       const char* a2 = last ? nA : cA + (size_t)(t + 2) * kstep; const char* b2 = last ? nB : cB + (size_t)(t + 2) * kstep;
;       const char* a3 = a2 + kstep; const char* b3 = b2 + kstep;
;     ...
; #pragma unroll
;     for (int a = 0; a < 2; ++a)
; #pragma unroll
;       for (int b = 0; b < 2; ++b)
; #pragma unroll
;         for (int m = 0; m < 4; ++m)
; #pragma unroll
;           for (int n = 0; n < 2; ++n) acc[a][b][m][n] = (f32x4){0.f, 0.f, 0.f, 0.f};
.LBB0_1481:
	v_mov_b64_e32 v[2:3], s[8:9]
	s_ashr_i32 s11, s10, 31
	v_cmp_lt_i64_e32 vcc, s[12:13], v[2:3]
	s_lshl_b64 s[12:13], s[10:11], 19
	s_add_u32 s12, s84, s12
	s_addc_u32 s13, s85, s13
	s_and_b64 s[14:15], vcc, exec
	s_cselect_b32 s11, s13, s19
	s_cselect_b32 s50, s12, s18
	s_ashr_i32 s1, s0, 31
	s_lshl_b64 s[14:15], s[0:1], 19
	s_add_u32 s14, s30, s14
	s_addc_u32 s15, s31, s15
	s_and_b64 s[22:23], vcc, exec
	s_cselect_b32 s1, s15, s21
	s_cselect_b32 s51, s14, s20
	s_add_u32 s52, s20, 0x100
	v_mov_b32_e32 v2, 0
	s_addc_u32 s53, s21, 0
	s_mov_b32 s54, -2
	v_mov_b32_e32 v3, v2
	v_mov_b64_e32 v[4:5], 0
	v_mov_b64_e32 v[6:7], 0
	v_mov_b64_e32 v[8:9], 0
	v_mov_b64_e32 v[10:11], 0
	v_mov_b64_e32 v[12:13], 0
	v_mov_b64_e32 v[14:15], 0
	v_mov_b64_e32 v[16:17], 0
	v_mov_b64_e32 v[18:19], 0
	v_mov_b64_e32 v[20:21], 0
	v_mov_b64_e32 v[22:23], 0
	v_mov_b64_e32 v[24:25], 0
	v_mov_b64_e32 v[26:27], 0
	v_mov_b64_e32 v[28:29], 0
	v_mov_b64_e32 v[30:31], 0
	v_mov_b64_e32 v[32:33], 0
	v_mov_b64_e32 v[34:35], 0
	v_mov_b64_e32 v[36:37], 0
	v_mov_b64_e32 v[38:39], 0
	v_mov_b64_e32 v[40:41], 0
	v_mov_b64_e32 v[42:43], 0
	v_mov_b64_e32 v[44:45], 0
	v_mov_b64_e32 v[46:47], 0
	v_mov_b64_e32 v[48:49], 0
	v_mov_b64_e32 v[50:51], 0
	v_mov_b64_e32 v[52:53], 0
	v_mov_b64_e32 v[54:55], 0
	v_mov_b64_e32 v[56:57], 0
	v_mov_b64_e32 v[58:59], 0
	v_mov_b64_e32 v[60:61], 0
	v_mov_b64_e32 v[62:63], 0
	v_mov_b64_e32 v[64:65], 0
	v_mov_b64_e32 v[66:67], 0
	v_mov_b64_e32 v[68:69], 0
	v_mov_b64_e32 v[70:71], 0
	v_mov_b64_e32 v[72:73], 0
	v_mov_b64_e32 v[74:75], 0
	v_mov_b64_e32 v[76:77], 0
	v_mov_b64_e32 v[78:79], 0
	v_mov_b64_e32 v[80:81], 0
	v_mov_b64_e32 v[82:83], 0
	v_mov_b64_e32 v[84:85], 0
	v_mov_b64_e32 v[86:87], 0
	v_mov_b64_e32 v[88:89], 0
	v_mov_b64_e32 v[90:91], 0
	v_mov_b64_e32 v[92:93], 0
	v_mov_b64_e32 v[94:95], 0
	v_mov_b64_e32 v[96:97], 0
	v_mov_b64_e32 v[98:99], 0
	v_mov_b64_e32 v[100:101], 0
	v_mov_b64_e32 v[102:103], 0
	v_mov_b64_e32 v[104:105], 0
	v_mov_b64_e32 v[106:107], 0
	v_mov_b64_e32 v[108:109], 0
	v_mov_b64_e32 v[110:111], 0
	v_mov_b64_e32 v[112:113], 0
	v_mov_b64_e32 v[114:115], 0
	v_mov_b64_e32 v[116:117], 0
	v_mov_b64_e32 v[118:119], 0
	v_mov_b64_e32 v[120:121], 0
	v_mov_b64_e32 v[122:123], 0
	v_mov_b64_e32 v[124:125], 0
	v_mov_b64_e32 v[126:127], 0
	v_mov_b64_e32 v[128:129], 0

;   __device__ __forceinline__ const char* aptr(const Unit& u) const { return s.aptr(u); }
;   __device__ __forceinline__ const char* bptr(const Unit& u) const { return s.bptr(u); }
;   __device__ __forceinline__ bool next(int i, Unit& u) const { if (i) return false; u = u0; return true; }
; template <class Epi, class Sched>
; __device__ __forceinline__ void gemm_phase(PG8_LAS unsigned char* lds, const int lda, const int ldb, const Sched& S, const Epi& E) {
;     ...
;     const bool has_next = S.next(ui + 1, nxt);
;     const char* nA = has_next ? S.aptr(nxt) : cA; const char* nB = has_next ? S.bptr(nxt) : cB;
; #pragma unroll 1
;     for (int t = 0; t < nt; t += 2) {
;       const bool last = (t == nt - 2);
;       const char* a1 = cA + (size_t)(t + 1) * kstep;
;       const char* a2 = last ? nA : cA + (size_t)(t + 2) * kstep; const char* b2 = last ? nB : cB + (size_t)(t + 2) * kstep;
;       const char* a3 = a2 + kstep; const char* b3 = b2 + kstep;
;     ...
; #pragma unroll
;     for (int a = 0; a < 2; ++a)
; #pragma unroll
;       for (int b = 0; b < 2; ++b)
; #pragma unroll
;         for (int m = 0; m < 4; ++m)
; #pragma unroll
;           for (int n = 0; n < 2; ++n) acc[a][b][m][n] = (f32x4){0.f, 0.f, 0.f, 0.f};
.LBB0_1603:
	v_mov_b64_e32 v[2:3], s[2:3]
	s_ashr_i32 s11, s10, 31
	v_cmp_lt_i64_e32 vcc, s[12:13], v[2:3]
	s_lshl_b64 s[12:13], s[10:11], 19
	s_add_u32 s12, s58, s12
	s_addc_u32 s13, s59, s13
	s_and_b64 s[14:15], vcc, exec
	s_cselect_b32 s11, s13, s19
	s_cselect_b32 s42, s12, s18
	s_ashr_i32 s1, s0, 31
	s_lshl_b64 s[14:15], s[0:1], 19
	s_add_u32 s14, s24, s14
	s_addc_u32 s15, s25, s15
	s_and_b64 s[22:23], vcc, exec
	s_cselect_b32 s1, s15, s21
	s_cselect_b32 s43, s14, s20
	s_add_u32 s18, s18, 0x40080
	s_addc_u32 s19, s19, 0
	s_add_u32 s44, s20, 0x100
	v_mov_b32_e32 v2, 0
	s_addc_u32 s45, s21, 0
	s_mov_b32 s46, -2
	v_mov_b32_e32 v3, v2
	v_mov_b64_e32 v[4:5], 0
	v_mov_b64_e32 v[6:7], 0
	v_mov_b64_e32 v[8:9], 0
	v_mov_b64_e32 v[10:11], 0
	v_mov_b64_e32 v[12:13], 0
	v_mov_b64_e32 v[14:15], 0
	v_mov_b64_e32 v[16:17], 0
	v_mov_b64_e32 v[18:19], 0
	v_mov_b64_e32 v[20:21], 0
	v_mov_b64_e32 v[22:23], 0
	v_mov_b64_e32 v[24:25], 0
	v_mov_b64_e32 v[26:27], 0
	v_mov_b64_e32 v[28:29], 0
	v_mov_b64_e32 v[30:31], 0
	v_mov_b64_e32 v[32:33], 0
	v_mov_b64_e32 v[34:35], 0
	v_mov_b64_e32 v[36:37], 0
	v_mov_b64_e32 v[38:39], 0
	v_mov_b64_e32 v[40:41], 0
	v_mov_b64_e32 v[42:43], 0
	v_mov_b64_e32 v[44:45], 0
	v_mov_b64_e32 v[46:47], 0
	v_mov_b64_e32 v[48:49], 0
	v_mov_b64_e32 v[50:51], 0
	v_mov_b64_e32 v[52:53], 0
	v_mov_b64_e32 v[54:55], 0
	v_mov_b64_e32 v[56:57], 0
	v_mov_b64_e32 v[58:59], 0
	v_mov_b64_e32 v[60:61], 0
	v_mov_b64_e32 v[62:63], 0
	v_mov_b64_e32 v[64:65], 0
	v_mov_b64_e32 v[66:67], 0
	v_mov_b64_e32 v[68:69], 0
	v_mov_b64_e32 v[70:71], 0
	v_mov_b64_e32 v[72:73], 0
	v_mov_b64_e32 v[74:75], 0
	v_mov_b64_e32 v[76:77], 0
	v_mov_b64_e32 v[78:79], 0
	v_mov_b64_e32 v[80:81], 0
	v_mov_b64_e32 v[82:83], 0
	v_mov_b64_e32 v[84:85], 0
	v_mov_b64_e32 v[86:87], 0
	v_mov_b64_e32 v[88:89], 0
	v_mov_b64_e32 v[90:91], 0
	v_mov_b64_e32 v[92:93], 0
	v_mov_b64_e32 v[94:95], 0
	v_mov_b64_e32 v[96:97], 0
	v_mov_b64_e32 v[98:99], 0
	v_mov_b64_e32 v[100:101], 0
	v_mov_b64_e32 v[102:103], 0
	v_mov_b64_e32 v[104:105], 0
	v_mov_b64_e32 v[106:107], 0
	v_mov_b64_e32 v[108:109], 0
	v_mov_b64_e32 v[110:111], 0
	v_mov_b64_e32 v[112:113], 0
	v_mov_b64_e32 v[114:115], 0
	v_mov_b64_e32 v[116:117], 0
	v_mov_b64_e32 v[118:119], 0
	v_mov_b64_e32 v[120:121], 0
	v_mov_b64_e32 v[122:123], 0
	v_mov_b64_e32 v[124:125], 0
	v_mov_b64_e32 v[126:127], 0
	v_mov_b64_e32 v[128:129], 0

;   __device__ __forceinline__ int kt(const Unit& u) const { return ((u.pn & 7) < 4) ? 4 : 16; }
; template <class Epi, class Sched>
; __device__ __forceinline__ void gemm_phase(PG8_LAS unsigned char* lds, const int lda, const int ldb, const Sched& S, const Epi& E) {
;     ...
; #pragma unroll
;     for (int a = 0; a < 2; ++a)
; #pragma unroll
;       for (int b = 0; b < 2; ++b)
; #pragma unroll
;         for (int m = 0; m < 4; ++m)
; #pragma unroll
;           for (int n = 0; n < 2; ++n) acc[a][b][m][n] = (f32x4){0.f, 0.f, 0.f, 0.f};
;     cur = nxt; cA = nA; cB = nB; ++ui;
;     nt = S.kt(cur);
.LBB0_1672:
	s_add_u32 s39, s12, 0x100
	v_mov_b32_e32 v2, 0
	s_addc_u32 s40, s13, 0
	s_mov_b32 s41, -2
	v_mov_b32_e32 v3, v2
	v_mov_b64_e32 v[4:5], 0
	v_mov_b64_e32 v[6:7], 0
	v_mov_b64_e32 v[8:9], 0
	v_mov_b64_e32 v[10:11], 0
	v_mov_b64_e32 v[12:13], 0
	v_mov_b64_e32 v[14:15], 0
	v_mov_b64_e32 v[16:17], 0
	v_mov_b64_e32 v[18:19], 0
	v_mov_b64_e32 v[20:21], 0
	v_mov_b64_e32 v[22:23], 0
	v_mov_b64_e32 v[24:25], 0
	v_mov_b64_e32 v[26:27], 0
	v_mov_b64_e32 v[28:29], 0
	v_mov_b64_e32 v[30:31], 0
	v_mov_b64_e32 v[32:33], 0
	v_mov_b64_e32 v[34:35], 0
	v_mov_b64_e32 v[36:37], 0
	v_mov_b64_e32 v[38:39], 0
	v_mov_b64_e32 v[40:41], 0
	v_mov_b64_e32 v[42:43], 0
	v_mov_b64_e32 v[44:45], 0
	v_mov_b64_e32 v[46:47], 0
	v_mov_b64_e32 v[48:49], 0
	v_mov_b64_e32 v[50:51], 0
	v_mov_b64_e32 v[52:53], 0
	v_mov_b64_e32 v[54:55], 0
	v_mov_b64_e32 v[56:57], 0
	v_mov_b64_e32 v[58:59], 0
	v_mov_b64_e32 v[60:61], 0
	v_mov_b64_e32 v[62:63], 0
	v_mov_b64_e32 v[64:65], 0
	v_mov_b64_e32 v[66:67], 0
	v_mov_b64_e32 v[68:69], 0
	v_mov_b64_e32 v[70:71], 0
	v_mov_b64_e32 v[72:73], 0
	v_mov_b64_e32 v[74:75], 0
	v_mov_b64_e32 v[76:77], 0
	v_mov_b64_e32 v[78:79], 0
	v_mov_b64_e32 v[80:81], 0
	v_mov_b64_e32 v[82:83], 0
	v_mov_b64_e32 v[84:85], 0
	v_mov_b64_e32 v[86:87], 0
	v_mov_b64_e32 v[88:89], 0
	v_mov_b64_e32 v[90:91], 0
	v_mov_b64_e32 v[92:93], 0
	v_mov_b64_e32 v[94:95], 0
	v_mov_b64_e32 v[96:97], 0
	v_mov_b64_e32 v[98:99], 0
	v_mov_b64_e32 v[100:101], 0
	v_mov_b64_e32 v[102:103], 0
	v_mov_b64_e32 v[104:105], 0
	v_mov_b64_e32 v[106:107], 0
	v_mov_b64_e32 v[108:109], 0
	v_mov_b64_e32 v[110:111], 0
	v_mov_b64_e32 v[112:113], 0
	v_mov_b64_e32 v[114:115], 0
	v_mov_b64_e32 v[116:117], 0
	v_mov_b64_e32 v[118:119], 0
	v_mov_b64_e32 v[120:121], 0
	v_mov_b64_e32 v[122:123], 0
	v_mov_b64_e32 v[124:125], 0
	v_mov_b64_e32 v[126:127], 0
	v_mov_b64_e32 v[128:129], 0
